# pooled-branch weight fold hand-written: LDS rows interleaved (one ds_read_b128 per d feeds two packed fmas), 32-deep rolling column loads with SALU-advanced base
# speedup vs baseline: 1.0111x; 1.0070x over previous
; #define LAS __attribute__((address_space(3)))
; #define LDS_WAIT() asm volatile("s_waitcnt lgkmcnt(0)" ::: "memory")
; __global__ void __launch_bounds__(NTHREADS, 2) mk_fwd(Args args) {
;     ...
;             for (int it = gw; it < 128 * 16; it += NGW) {
;                 const int kb = it >> 4, nb = it & 15, k0 = kb * 4, g = k0 >> 7, c0 = k0 & 127, n = nb * 64 + lane;
;                 { const f32x2 sc = *(const f32x2*)(psc + g * 128 + 2 * lane);
; #pragma unroll
;                   for (int j = 0; j < 4; ++j) { const f32x2 v = *(const f32x2*)(pw + (size_t)(g * 128 + c0 + j) * 128 + 2 * lane); *(LAS f32x2*)(scr + j * 128 + 2 * lane) = (f32x2){v.x * sc.x, v.y * sc.y}; } }
;                 LDS_WAIT(); asm volatile("" ::: "memory");
;                 float a4[4];
; #pragma unroll
;                 for (int j = 0; j < 4; ++j) a4[j] = 0.f;
; #pragma unroll 1
;                 for (int d0 = 0; d0 < 128; d0 += 32) {
;                     float wv[32];
; #pragma unroll
;                     for (int d = 0; d < 32; ++d) wv[d] = wpo[(size_t)(g * 128 + d0 + d) * DM + n];
; #pragma unroll
;                     for (int d = 0; d < 32; d += 4)
; #pragma unroll
;                         for (int j = 0; j < 4; ++j) { const f32x4 pv = *(const LAS f32x4*)(scr + j * 128 + d0 + d); a4[j] += (pv.x * wv[d] + pv.y * wv[d + 1]) + (pv.z * wv[d + 2] + pv.w * wv[d + 3]); } }
.LBB0_617:
	s_lshl_b32 s2, s14, 2
	s_and_b32 s2, s2, 0xf00
	s_ashr_i32 s17, s15, 2
	v_lshl_or_b32 v32, v71, 2, s2
	s_and_b32 s2, s17, -4
	s_ashr_i32 s3, s2, 31
	s_lshl_b64 s[20:21], s[2:3], 9
	s_and_b32 s18, s17, 0xffffff80
	s_ashr_i32 s19, s18, 31
	v_lshl_add_u64 v[64:65], v[36:37], 0, s[20:21]
	v_lshl_add_u64 v[66:67], s[18:19], 2, v[34:35]
	global_load_dwordx2 v[38:39], v[66:67], off
	global_load_dwordx2 v[46:47], v[64:65], off
	global_load_dwordx2 v[48:49], v[64:65], off offset:512
	global_load_dwordx2 v[50:51], v[64:65], off offset:1024
	global_load_dwordx2 v[52:53], v[64:65], off offset:1536
	s_lshl_b64 s[18:19], s[18:19], 12
	s_add_u32 s18, s12, s18
	s_addc_u32 s19, s13, s19
	v_lshl_add_u32 v62, v71, 5, s34
	v_mov_b32_e32 v63, s34
	v_mov_b32_e32 v40, 0
	v_mov_b32_e32 v41, 0
	v_mov_b32_e32 v42, 0
	v_mov_b32_e32 v43, 0
	global_load_dword v82, v32, s[18:19]
	s_add_u32 s18, s18, 0x1000
	s_addc_u32 s19, s19, 0
	global_load_dword v83, v32, s[18:19]
	s_add_u32 s18, s18, 0x1000
	s_addc_u32 s19, s19, 0
	global_load_dword v84, v32, s[18:19]
	s_add_u32 s18, s18, 0x1000
	s_addc_u32 s19, s19, 0
	global_load_dword v85, v32, s[18:19]
	s_add_u32 s18, s18, 0x1000
	s_addc_u32 s19, s19, 0
	global_load_dword v86, v32, s[18:19]
	s_add_u32 s18, s18, 0x1000
	s_addc_u32 s19, s19, 0
	global_load_dword v87, v32, s[18:19]
	s_add_u32 s18, s18, 0x1000
	s_addc_u32 s19, s19, 0
	global_load_dword v88, v32, s[18:19]
	s_add_u32 s18, s18, 0x1000
	s_addc_u32 s19, s19, 0
	global_load_dword v89, v32, s[18:19]
	s_add_u32 s18, s18, 0x1000
	s_addc_u32 s19, s19, 0
	global_load_dword v90, v32, s[18:19]
	s_add_u32 s18, s18, 0x1000
	s_addc_u32 s19, s19, 0
	global_load_dword v91, v32, s[18:19]
	s_add_u32 s18, s18, 0x1000
	s_addc_u32 s19, s19, 0
	global_load_dword v92, v32, s[18:19]
	s_add_u32 s18, s18, 0x1000
	s_addc_u32 s19, s19, 0
	global_load_dword v93, v32, s[18:19]
	s_add_u32 s18, s18, 0x1000
	s_addc_u32 s19, s19, 0
	global_load_dword v94, v32, s[18:19]
	s_add_u32 s18, s18, 0x1000
	s_addc_u32 s19, s19, 0
	global_load_dword v95, v32, s[18:19]
	s_add_u32 s18, s18, 0x1000
	s_addc_u32 s19, s19, 0
	global_load_dword v96, v32, s[18:19]
	s_add_u32 s18, s18, 0x1000
	s_addc_u32 s19, s19, 0
	global_load_dword v97, v32, s[18:19]
	s_add_u32 s18, s18, 0x1000
	s_addc_u32 s19, s19, 0
	global_load_dword v98, v32, s[18:19]
	s_add_u32 s18, s18, 0x1000
	s_addc_u32 s19, s19, 0
	global_load_dword v99, v32, s[18:19]
	s_add_u32 s18, s18, 0x1000
	s_addc_u32 s19, s19, 0
	global_load_dword v100, v32, s[18:19]
	s_add_u32 s18, s18, 0x1000
	s_addc_u32 s19, s19, 0
	global_load_dword v101, v32, s[18:19]
	s_add_u32 s18, s18, 0x1000
	s_addc_u32 s19, s19, 0
	global_load_dword v102, v32, s[18:19]
	s_add_u32 s18, s18, 0x1000
	s_addc_u32 s19, s19, 0
	global_load_dword v103, v32, s[18:19]
	s_add_u32 s18, s18, 0x1000
	s_addc_u32 s19, s19, 0
	global_load_dword v104, v32, s[18:19]
	s_add_u32 s18, s18, 0x1000
	s_addc_u32 s19, s19, 0
	global_load_dword v105, v32, s[18:19]
	s_add_u32 s18, s18, 0x1000
	s_addc_u32 s19, s19, 0
	global_load_dword v106, v32, s[18:19]
	s_add_u32 s18, s18, 0x1000
	s_addc_u32 s19, s19, 0
	global_load_dword v107, v32, s[18:19]
	s_add_u32 s18, s18, 0x1000
	s_addc_u32 s19, s19, 0
	global_load_dword v108, v32, s[18:19]
	s_add_u32 s18, s18, 0x1000
	s_addc_u32 s19, s19, 0
	global_load_dword v109, v32, s[18:19]
	s_add_u32 s18, s18, 0x1000
	s_addc_u32 s19, s19, 0
	global_load_dword v110, v32, s[18:19]
	s_add_u32 s18, s18, 0x1000
	s_addc_u32 s19, s19, 0
	global_load_dword v111, v32, s[18:19]
	s_add_u32 s18, s18, 0x1000
	s_addc_u32 s19, s19, 0
	global_load_dword v112, v32, s[18:19]
	s_add_u32 s18, s18, 0x1000
	s_addc_u32 s19, s19, 0
	global_load_dword v113, v32, s[18:19]
	s_add_u32 s18, s18, 0x1000
	s_addc_u32 s19, s19, 0
	s_waitcnt vmcnt(32)
	v_mul_f32_e32 v54, v38, v46
	v_mul_f32_e32 v58, v39, v47
	v_mul_f32_e32 v55, v38, v48
	v_mul_f32_e32 v59, v39, v49
	v_mul_f32_e32 v56, v38, v50
	v_mul_f32_e32 v60, v39, v51
	v_mul_f32_e32 v57, v38, v52
	v_mul_f32_e32 v61, v39, v53
	ds_write_b128 v62, v[54:57]
	ds_write_b128 v62, v[58:61] offset:16
	s_waitcnt lgkmcnt(0)
	ds_read_b128 v[114:117], v63 offset:0
	ds_read_b128 v[118:121], v63 offset:16
	ds_read_b128 v[122:125], v63 offset:32
	ds_read_b128 v[126:129], v63 offset:48
	s_waitcnt vmcnt(31) lgkmcnt(3)
	v_pk_fma_f32 v[40:41], v[114:115], v[82:83], v[40:41] op_sel_hi:[1,0,1]
	v_pk_fma_f32 v[42:43], v[116:117], v[82:83], v[42:43] op_sel_hi:[1,0,1]
	global_load_dword v82, v32, s[18:19]
	s_add_u32 s18, s18, 0x1000
	s_addc_u32 s19, s19, 0
	ds_read_b128 v[114:117], v63 offset:64
	s_waitcnt vmcnt(31) lgkmcnt(3)
	v_pk_fma_f32 v[40:41], v[118:119], v[82:83], v[40:41] op_sel:[0,1,0] op_sel_hi:[1,1,1]
	v_pk_fma_f32 v[42:43], v[120:121], v[82:83], v[42:43] op_sel:[0,1,0] op_sel_hi:[1,1,1]
	global_load_dword v83, v32, s[18:19]
	s_add_u32 s18, s18, 0x1000
	s_addc_u32 s19, s19, 0
	ds_read_b128 v[118:121], v63 offset:80
	s_waitcnt vmcnt(31) lgkmcnt(3)
	v_pk_fma_f32 v[40:41], v[122:123], v[84:85], v[40:41] op_sel_hi:[1,0,1]
	v_pk_fma_f32 v[42:43], v[124:125], v[84:85], v[42:43] op_sel_hi:[1,0,1]
	global_load_dword v84, v32, s[18:19]
	s_add_u32 s18, s18, 0x1000
	s_addc_u32 s19, s19, 0
	ds_read_b128 v[122:125], v63 offset:96
	s_waitcnt vmcnt(31) lgkmcnt(3)
	v_pk_fma_f32 v[40:41], v[126:127], v[84:85], v[40:41] op_sel:[0,1,0] op_sel_hi:[1,1,1]
	v_pk_fma_f32 v[42:43], v[128:129], v[84:85], v[42:43] op_sel:[0,1,0] op_sel_hi:[1,1,1]
	global_load_dword v85, v32, s[18:19]
	s_add_u32 s18, s18, 0x1000
	s_addc_u32 s19, s19, 0
	ds_read_b128 v[126:129], v63 offset:112
	s_waitcnt vmcnt(31) lgkmcnt(3)
; #define LAS __attribute__((address_space(3)))
; __global__ void __launch_bounds__(NTHREADS, 2) mk_fwd(Args args) {
;     ...
;                 for (int d0 = 0; d0 < 128; d0 += 32) {
;                     float wv[32];
; #pragma unroll
;                     for (int d = 0; d < 32; ++d) wv[d] = wpo[(size_t)(g * 128 + d0 + d) * DM + n];
; #pragma unroll
;                     for (int d = 0; d < 32; d += 4)
; #pragma unroll
;                         for (int j = 0; j < 4; ++j) { const f32x4 pv = *(const LAS f32x4*)(scr + j * 128 + d0 + d); a4[j] += (pv.x * wv[d] + pv.y * wv[d + 1]) + (pv.z * wv[d + 2] + pv.w * wv[d + 3]); } }
	v_pk_fma_f32 v[40:41], v[114:115], v[86:87], v[40:41] op_sel_hi:[1,0,1]
	v_pk_fma_f32 v[42:43], v[116:117], v[86:87], v[42:43] op_sel_hi:[1,0,1]
	global_load_dword v86, v32, s[18:19]
	s_add_u32 s18, s18, 0x1000
	s_addc_u32 s19, s19, 0
	ds_read_b128 v[114:117], v63 offset:128
	s_waitcnt vmcnt(31) lgkmcnt(3)
	v_pk_fma_f32 v[40:41], v[118:119], v[86:87], v[40:41] op_sel:[0,1,0] op_sel_hi:[1,1,1]
	v_pk_fma_f32 v[42:43], v[120:121], v[86:87], v[42:43] op_sel:[0,1,0] op_sel_hi:[1,1,1]
	global_load_dword v87, v32, s[18:19]
	s_add_u32 s18, s18, 0x1000
	s_addc_u32 s19, s19, 0
	ds_read_b128 v[118:121], v63 offset:144
	s_waitcnt vmcnt(31) lgkmcnt(3)
	v_pk_fma_f32 v[40:41], v[122:123], v[88:89], v[40:41] op_sel_hi:[1,0,1]
	v_pk_fma_f32 v[42:43], v[124:125], v[88:89], v[42:43] op_sel_hi:[1,0,1]
	global_load_dword v88, v32, s[18:19]
	s_add_u32 s18, s18, 0x1000
	s_addc_u32 s19, s19, 0
	ds_read_b128 v[122:125], v63 offset:160
	s_waitcnt vmcnt(31) lgkmcnt(3)
	v_pk_fma_f32 v[40:41], v[126:127], v[88:89], v[40:41] op_sel:[0,1,0] op_sel_hi:[1,1,1]
	v_pk_fma_f32 v[42:43], v[128:129], v[88:89], v[42:43] op_sel:[0,1,0] op_sel_hi:[1,1,1]
	global_load_dword v89, v32, s[18:19]
	s_add_u32 s18, s18, 0x1000
	s_addc_u32 s19, s19, 0
	ds_read_b128 v[126:129], v63 offset:176
	s_waitcnt vmcnt(31) lgkmcnt(3)
	v_pk_fma_f32 v[40:41], v[114:115], v[90:91], v[40:41] op_sel_hi:[1,0,1]
	v_pk_fma_f32 v[42:43], v[116:117], v[90:91], v[42:43] op_sel_hi:[1,0,1]
	global_load_dword v90, v32, s[18:19]
	s_add_u32 s18, s18, 0x1000
	s_addc_u32 s19, s19, 0
	ds_read_b128 v[114:117], v63 offset:192
	s_waitcnt vmcnt(31) lgkmcnt(3)
	v_pk_fma_f32 v[40:41], v[118:119], v[90:91], v[40:41] op_sel:[0,1,0] op_sel_hi:[1,1,1]
	v_pk_fma_f32 v[42:43], v[120:121], v[90:91], v[42:43] op_sel:[0,1,0] op_sel_hi:[1,1,1]
	global_load_dword v91, v32, s[18:19]
	s_add_u32 s18, s18, 0x1000
	s_addc_u32 s19, s19, 0
	ds_read_b128 v[118:121], v63 offset:208
	s_waitcnt vmcnt(31) lgkmcnt(3)
	v_pk_fma_f32 v[40:41], v[122:123], v[92:93], v[40:41] op_sel_hi:[1,0,1]
	v_pk_fma_f32 v[42:43], v[124:125], v[92:93], v[42:43] op_sel_hi:[1,0,1]
	global_load_dword v92, v32, s[18:19]
	s_add_u32 s18, s18, 0x1000
	s_addc_u32 s19, s19, 0
	ds_read_b128 v[122:125], v63 offset:224
	s_waitcnt vmcnt(31) lgkmcnt(3)
	v_pk_fma_f32 v[40:41], v[126:127], v[92:93], v[40:41] op_sel:[0,1,0] op_sel_hi:[1,1,1]
	v_pk_fma_f32 v[42:43], v[128:129], v[92:93], v[42:43] op_sel:[0,1,0] op_sel_hi:[1,1,1]
	global_load_dword v93, v32, s[18:19]
	s_add_u32 s18, s18, 0x1000
	s_addc_u32 s19, s19, 0
	ds_read_b128 v[126:129], v63 offset:240
	s_waitcnt vmcnt(31) lgkmcnt(3)
	v_pk_fma_f32 v[40:41], v[114:115], v[94:95], v[40:41] op_sel_hi:[1,0,1]
	v_pk_fma_f32 v[42:43], v[116:117], v[94:95], v[42:43] op_sel_hi:[1,0,1]
	global_load_dword v94, v32, s[18:19]
	s_add_u32 s18, s18, 0x1000
	s_addc_u32 s19, s19, 0
	ds_read_b128 v[114:117], v63 offset:256
	s_waitcnt vmcnt(31) lgkmcnt(3)
	v_pk_fma_f32 v[40:41], v[118:119], v[94:95], v[40:41] op_sel:[0,1,0] op_sel_hi:[1,1,1]
	v_pk_fma_f32 v[42:43], v[120:121], v[94:95], v[42:43] op_sel:[0,1,0] op_sel_hi:[1,1,1]
	global_load_dword v95, v32, s[18:19]
	s_add_u32 s18, s18, 0x1000
	s_addc_u32 s19, s19, 0
	ds_read_b128 v[118:121], v63 offset:272
	s_waitcnt vmcnt(31) lgkmcnt(3)
	v_pk_fma_f32 v[40:41], v[122:123], v[96:97], v[40:41] op_sel_hi:[1,0,1]
	v_pk_fma_f32 v[42:43], v[124:125], v[96:97], v[42:43] op_sel_hi:[1,0,1]
	global_load_dword v96, v32, s[18:19]
	s_add_u32 s18, s18, 0x1000
	s_addc_u32 s19, s19, 0
	ds_read_b128 v[122:125], v63 offset:288
	s_waitcnt vmcnt(31) lgkmcnt(3)
	v_pk_fma_f32 v[40:41], v[126:127], v[96:97], v[40:41] op_sel:[0,1,0] op_sel_hi:[1,1,1]
	v_pk_fma_f32 v[42:43], v[128:129], v[96:97], v[42:43] op_sel:[0,1,0] op_sel_hi:[1,1,1]
	global_load_dword v97, v32, s[18:19]
	s_add_u32 s18, s18, 0x1000
	s_addc_u32 s19, s19, 0
	ds_read_b128 v[126:129], v63 offset:304
	s_waitcnt vmcnt(31) lgkmcnt(3)
	v_pk_fma_f32 v[40:41], v[114:115], v[98:99], v[40:41] op_sel_hi:[1,0,1]
	v_pk_fma_f32 v[42:43], v[116:117], v[98:99], v[42:43] op_sel_hi:[1,0,1]
	global_load_dword v98, v32, s[18:19]
	s_add_u32 s18, s18, 0x1000
	s_addc_u32 s19, s19, 0
	ds_read_b128 v[114:117], v63 offset:320
	s_waitcnt vmcnt(31) lgkmcnt(3)
	v_pk_fma_f32 v[40:41], v[118:119], v[98:99], v[40:41] op_sel:[0,1,0] op_sel_hi:[1,1,1]
	v_pk_fma_f32 v[42:43], v[120:121], v[98:99], v[42:43] op_sel:[0,1,0] op_sel_hi:[1,1,1]
	global_load_dword v99, v32, s[18:19]
	s_add_u32 s18, s18, 0x1000
	s_addc_u32 s19, s19, 0
	ds_read_b128 v[118:121], v63 offset:336
	s_waitcnt vmcnt(31) lgkmcnt(3)
	v_pk_fma_f32 v[40:41], v[122:123], v[100:101], v[40:41] op_sel_hi:[1,0,1]
	v_pk_fma_f32 v[42:43], v[124:125], v[100:101], v[42:43] op_sel_hi:[1,0,1]
	global_load_dword v100, v32, s[18:19]
	s_add_u32 s18, s18, 0x1000
	s_addc_u32 s19, s19, 0
	ds_read_b128 v[122:125], v63 offset:352
	s_waitcnt vmcnt(31) lgkmcnt(3)
	v_pk_fma_f32 v[40:41], v[126:127], v[100:101], v[40:41] op_sel:[0,1,0] op_sel_hi:[1,1,1]
	v_pk_fma_f32 v[42:43], v[128:129], v[100:101], v[42:43] op_sel:[0,1,0] op_sel_hi:[1,1,1]
	global_load_dword v101, v32, s[18:19]
	s_add_u32 s18, s18, 0x1000
	s_addc_u32 s19, s19, 0
	ds_read_b128 v[126:129], v63 offset:368
	s_waitcnt vmcnt(31) lgkmcnt(3)
	v_pk_fma_f32 v[40:41], v[114:115], v[102:103], v[40:41] op_sel_hi:[1,0,1]
	v_pk_fma_f32 v[42:43], v[116:117], v[102:103], v[42:43] op_sel_hi:[1,0,1]
	global_load_dword v102, v32, s[18:19]
	s_add_u32 s18, s18, 0x1000
	s_addc_u32 s19, s19, 0
	ds_read_b128 v[114:117], v63 offset:384
	s_waitcnt vmcnt(31) lgkmcnt(3)
; #define LAS __attribute__((address_space(3)))
; __global__ void __launch_bounds__(NTHREADS, 2) mk_fwd(Args args) {
;     ...
;                 for (int d0 = 0; d0 < 128; d0 += 32) {
;                     float wv[32];
; #pragma unroll
;                     for (int d = 0; d < 32; ++d) wv[d] = wpo[(size_t)(g * 128 + d0 + d) * DM + n];
; #pragma unroll
;                     for (int d = 0; d < 32; d += 4)
; #pragma unroll
;                         for (int j = 0; j < 4; ++j) { const f32x4 pv = *(const LAS f32x4*)(scr + j * 128 + d0 + d); a4[j] += (pv.x * wv[d] + pv.y * wv[d + 1]) + (pv.z * wv[d + 2] + pv.w * wv[d + 3]); } }
	v_pk_fma_f32 v[40:41], v[118:119], v[102:103], v[40:41] op_sel:[0,1,0] op_sel_hi:[1,1,1]
	v_pk_fma_f32 v[42:43], v[120:121], v[102:103], v[42:43] op_sel:[0,1,0] op_sel_hi:[1,1,1]
	global_load_dword v103, v32, s[18:19]
	s_add_u32 s18, s18, 0x1000
	s_addc_u32 s19, s19, 0
	ds_read_b128 v[118:121], v63 offset:400
	s_waitcnt vmcnt(31) lgkmcnt(3)
	v_pk_fma_f32 v[40:41], v[122:123], v[104:105], v[40:41] op_sel_hi:[1,0,1]
	v_pk_fma_f32 v[42:43], v[124:125], v[104:105], v[42:43] op_sel_hi:[1,0,1]
	global_load_dword v104, v32, s[18:19]
	s_add_u32 s18, s18, 0x1000
	s_addc_u32 s19, s19, 0
	ds_read_b128 v[122:125], v63 offset:416
	s_waitcnt vmcnt(31) lgkmcnt(3)
	v_pk_fma_f32 v[40:41], v[126:127], v[104:105], v[40:41] op_sel:[0,1,0] op_sel_hi:[1,1,1]
	v_pk_fma_f32 v[42:43], v[128:129], v[104:105], v[42:43] op_sel:[0,1,0] op_sel_hi:[1,1,1]
	global_load_dword v105, v32, s[18:19]
	s_add_u32 s18, s18, 0x1000
	s_addc_u32 s19, s19, 0
	ds_read_b128 v[126:129], v63 offset:432
	s_waitcnt vmcnt(31) lgkmcnt(3)
	v_pk_fma_f32 v[40:41], v[114:115], v[106:107], v[40:41] op_sel_hi:[1,0,1]
	v_pk_fma_f32 v[42:43], v[116:117], v[106:107], v[42:43] op_sel_hi:[1,0,1]
	global_load_dword v106, v32, s[18:19]
	s_add_u32 s18, s18, 0x1000
	s_addc_u32 s19, s19, 0
	ds_read_b128 v[114:117], v63 offset:448
	s_waitcnt vmcnt(31) lgkmcnt(3)
	v_pk_fma_f32 v[40:41], v[118:119], v[106:107], v[40:41] op_sel:[0,1,0] op_sel_hi:[1,1,1]
	v_pk_fma_f32 v[42:43], v[120:121], v[106:107], v[42:43] op_sel:[0,1,0] op_sel_hi:[1,1,1]
	global_load_dword v107, v32, s[18:19]
	s_add_u32 s18, s18, 0x1000
	s_addc_u32 s19, s19, 0
	ds_read_b128 v[118:121], v63 offset:464
	s_waitcnt vmcnt(31) lgkmcnt(3)
	v_pk_fma_f32 v[40:41], v[122:123], v[108:109], v[40:41] op_sel_hi:[1,0,1]
	v_pk_fma_f32 v[42:43], v[124:125], v[108:109], v[42:43] op_sel_hi:[1,0,1]
	global_load_dword v108, v32, s[18:19]
	s_add_u32 s18, s18, 0x1000
	s_addc_u32 s19, s19, 0
	ds_read_b128 v[122:125], v63 offset:480
	s_waitcnt vmcnt(31) lgkmcnt(3)
	v_pk_fma_f32 v[40:41], v[126:127], v[108:109], v[40:41] op_sel:[0,1,0] op_sel_hi:[1,1,1]
	v_pk_fma_f32 v[42:43], v[128:129], v[108:109], v[42:43] op_sel:[0,1,0] op_sel_hi:[1,1,1]
	global_load_dword v109, v32, s[18:19]
	s_add_u32 s18, s18, 0x1000
	s_addc_u32 s19, s19, 0
	ds_read_b128 v[126:129], v63 offset:496
	s_waitcnt vmcnt(31) lgkmcnt(3)
	v_pk_fma_f32 v[40:41], v[114:115], v[110:111], v[40:41] op_sel_hi:[1,0,1]
	v_pk_fma_f32 v[42:43], v[116:117], v[110:111], v[42:43] op_sel_hi:[1,0,1]
	global_load_dword v110, v32, s[18:19]
	s_add_u32 s18, s18, 0x1000
	s_addc_u32 s19, s19, 0
	ds_read_b128 v[114:117], v63 offset:512
	s_waitcnt vmcnt(31) lgkmcnt(3)
	v_pk_fma_f32 v[40:41], v[118:119], v[110:111], v[40:41] op_sel:[0,1,0] op_sel_hi:[1,1,1]
	v_pk_fma_f32 v[42:43], v[120:121], v[110:111], v[42:43] op_sel:[0,1,0] op_sel_hi:[1,1,1]
	global_load_dword v111, v32, s[18:19]
	s_add_u32 s18, s18, 0x1000
	s_addc_u32 s19, s19, 0
	ds_read_b128 v[118:121], v63 offset:528
	s_waitcnt vmcnt(31) lgkmcnt(3)
	v_pk_fma_f32 v[40:41], v[122:123], v[112:113], v[40:41] op_sel_hi:[1,0,1]
	v_pk_fma_f32 v[42:43], v[124:125], v[112:113], v[42:43] op_sel_hi:[1,0,1]
	global_load_dword v112, v32, s[18:19]
	s_add_u32 s18, s18, 0x1000
	s_addc_u32 s19, s19, 0
	ds_read_b128 v[122:125], v63 offset:544
	s_waitcnt vmcnt(31) lgkmcnt(3)
	v_pk_fma_f32 v[40:41], v[126:127], v[112:113], v[40:41] op_sel:[0,1,0] op_sel_hi:[1,1,1]
	v_pk_fma_f32 v[42:43], v[128:129], v[112:113], v[42:43] op_sel:[0,1,0] op_sel_hi:[1,1,1]
	global_load_dword v113, v32, s[18:19]
	s_add_u32 s18, s18, 0x1000
	s_addc_u32 s19, s19, 0
	ds_read_b128 v[126:129], v63 offset:560
	s_waitcnt vmcnt(31) lgkmcnt(3)
	v_pk_fma_f32 v[40:41], v[114:115], v[82:83], v[40:41] op_sel_hi:[1,0,1]
	v_pk_fma_f32 v[42:43], v[116:117], v[82:83], v[42:43] op_sel_hi:[1,0,1]
	global_load_dword v82, v32, s[18:19]
	s_add_u32 s18, s18, 0x1000
	s_addc_u32 s19, s19, 0
	ds_read_b128 v[114:117], v63 offset:576
	s_waitcnt vmcnt(31) lgkmcnt(3)
	v_pk_fma_f32 v[40:41], v[118:119], v[82:83], v[40:41] op_sel:[0,1,0] op_sel_hi:[1,1,1]
	v_pk_fma_f32 v[42:43], v[120:121], v[82:83], v[42:43] op_sel:[0,1,0] op_sel_hi:[1,1,1]
	global_load_dword v83, v32, s[18:19]
	s_add_u32 s18, s18, 0x1000
	s_addc_u32 s19, s19, 0
	ds_read_b128 v[118:121], v63 offset:592
	s_waitcnt vmcnt(31) lgkmcnt(3)
	v_pk_fma_f32 v[40:41], v[122:123], v[84:85], v[40:41] op_sel_hi:[1,0,1]
	v_pk_fma_f32 v[42:43], v[124:125], v[84:85], v[42:43] op_sel_hi:[1,0,1]
	global_load_dword v84, v32, s[18:19]
	s_add_u32 s18, s18, 0x1000
	s_addc_u32 s19, s19, 0
	ds_read_b128 v[122:125], v63 offset:608
	s_waitcnt vmcnt(31) lgkmcnt(3)
	v_pk_fma_f32 v[40:41], v[126:127], v[84:85], v[40:41] op_sel:[0,1,0] op_sel_hi:[1,1,1]
	v_pk_fma_f32 v[42:43], v[128:129], v[84:85], v[42:43] op_sel:[0,1,0] op_sel_hi:[1,1,1]
	global_load_dword v85, v32, s[18:19]
	s_add_u32 s18, s18, 0x1000
	s_addc_u32 s19, s19, 0
	ds_read_b128 v[126:129], v63 offset:624
	s_waitcnt vmcnt(31) lgkmcnt(3)
	v_pk_fma_f32 v[40:41], v[114:115], v[86:87], v[40:41] op_sel_hi:[1,0,1]
	v_pk_fma_f32 v[42:43], v[116:117], v[86:87], v[42:43] op_sel_hi:[1,0,1]
	global_load_dword v86, v32, s[18:19]
	s_add_u32 s18, s18, 0x1000
	s_addc_u32 s19, s19, 0
	ds_read_b128 v[114:117], v63 offset:640
	s_waitcnt vmcnt(31) lgkmcnt(3)
	v_pk_fma_f32 v[40:41], v[118:119], v[86:87], v[40:41] op_sel:[0,1,0] op_sel_hi:[1,1,1]
	v_pk_fma_f32 v[42:43], v[120:121], v[86:87], v[42:43] op_sel:[0,1,0] op_sel_hi:[1,1,1]
	global_load_dword v87, v32, s[18:19]
	s_add_u32 s18, s18, 0x1000
	s_addc_u32 s19, s19, 0
	ds_read_b128 v[118:121], v63 offset:656
	s_waitcnt vmcnt(31) lgkmcnt(3)
; #define LAS __attribute__((address_space(3)))
; __global__ void __launch_bounds__(NTHREADS, 2) mk_fwd(Args args) {
;     ...
;                 for (int d0 = 0; d0 < 128; d0 += 32) {
;                     float wv[32];
; #pragma unroll
;                     for (int d = 0; d < 32; ++d) wv[d] = wpo[(size_t)(g * 128 + d0 + d) * DM + n];
; #pragma unroll
;                     for (int d = 0; d < 32; d += 4)
; #pragma unroll
;                         for (int j = 0; j < 4; ++j) { const f32x4 pv = *(const LAS f32x4*)(scr + j * 128 + d0 + d); a4[j] += (pv.x * wv[d] + pv.y * wv[d + 1]) + (pv.z * wv[d + 2] + pv.w * wv[d + 3]); } }
	v_pk_fma_f32 v[40:41], v[122:123], v[88:89], v[40:41] op_sel_hi:[1,0,1]
	v_pk_fma_f32 v[42:43], v[124:125], v[88:89], v[42:43] op_sel_hi:[1,0,1]
	global_load_dword v88, v32, s[18:19]
	s_add_u32 s18, s18, 0x1000
	s_addc_u32 s19, s19, 0
	ds_read_b128 v[122:125], v63 offset:672
	s_waitcnt vmcnt(31) lgkmcnt(3)
	v_pk_fma_f32 v[40:41], v[126:127], v[88:89], v[40:41] op_sel:[0,1,0] op_sel_hi:[1,1,1]
	v_pk_fma_f32 v[42:43], v[128:129], v[88:89], v[42:43] op_sel:[0,1,0] op_sel_hi:[1,1,1]
	global_load_dword v89, v32, s[18:19]
	s_add_u32 s18, s18, 0x1000
	s_addc_u32 s19, s19, 0
	ds_read_b128 v[126:129], v63 offset:688
	s_waitcnt vmcnt(31) lgkmcnt(3)
	v_pk_fma_f32 v[40:41], v[114:115], v[90:91], v[40:41] op_sel_hi:[1,0,1]
	v_pk_fma_f32 v[42:43], v[116:117], v[90:91], v[42:43] op_sel_hi:[1,0,1]
	global_load_dword v90, v32, s[18:19]
	s_add_u32 s18, s18, 0x1000
	s_addc_u32 s19, s19, 0
	ds_read_b128 v[114:117], v63 offset:704
	s_waitcnt vmcnt(31) lgkmcnt(3)
	v_pk_fma_f32 v[40:41], v[118:119], v[90:91], v[40:41] op_sel:[0,1,0] op_sel_hi:[1,1,1]
	v_pk_fma_f32 v[42:43], v[120:121], v[90:91], v[42:43] op_sel:[0,1,0] op_sel_hi:[1,1,1]
	global_load_dword v91, v32, s[18:19]
	s_add_u32 s18, s18, 0x1000
	s_addc_u32 s19, s19, 0
	ds_read_b128 v[118:121], v63 offset:720
	s_waitcnt vmcnt(31) lgkmcnt(3)
	v_pk_fma_f32 v[40:41], v[122:123], v[92:93], v[40:41] op_sel_hi:[1,0,1]
	v_pk_fma_f32 v[42:43], v[124:125], v[92:93], v[42:43] op_sel_hi:[1,0,1]
	global_load_dword v92, v32, s[18:19]
	s_add_u32 s18, s18, 0x1000
	s_addc_u32 s19, s19, 0
	ds_read_b128 v[122:125], v63 offset:736
	s_waitcnt vmcnt(31) lgkmcnt(3)
	v_pk_fma_f32 v[40:41], v[126:127], v[92:93], v[40:41] op_sel:[0,1,0] op_sel_hi:[1,1,1]
	v_pk_fma_f32 v[42:43], v[128:129], v[92:93], v[42:43] op_sel:[0,1,0] op_sel_hi:[1,1,1]
	global_load_dword v93, v32, s[18:19]
	s_add_u32 s18, s18, 0x1000
	s_addc_u32 s19, s19, 0
	ds_read_b128 v[126:129], v63 offset:752
	s_waitcnt vmcnt(31) lgkmcnt(3)
	v_pk_fma_f32 v[40:41], v[114:115], v[94:95], v[40:41] op_sel_hi:[1,0,1]
	v_pk_fma_f32 v[42:43], v[116:117], v[94:95], v[42:43] op_sel_hi:[1,0,1]
	global_load_dword v94, v32, s[18:19]
	s_add_u32 s18, s18, 0x1000
	s_addc_u32 s19, s19, 0
	ds_read_b128 v[114:117], v63 offset:768
	s_waitcnt vmcnt(31) lgkmcnt(3)
	v_pk_fma_f32 v[40:41], v[118:119], v[94:95], v[40:41] op_sel:[0,1,0] op_sel_hi:[1,1,1]
	v_pk_fma_f32 v[42:43], v[120:121], v[94:95], v[42:43] op_sel:[0,1,0] op_sel_hi:[1,1,1]
	global_load_dword v95, v32, s[18:19]
	s_add_u32 s18, s18, 0x1000
	s_addc_u32 s19, s19, 0
	ds_read_b128 v[118:121], v63 offset:784
	s_waitcnt vmcnt(31) lgkmcnt(3)
	v_pk_fma_f32 v[40:41], v[122:123], v[96:97], v[40:41] op_sel_hi:[1,0,1]
	v_pk_fma_f32 v[42:43], v[124:125], v[96:97], v[42:43] op_sel_hi:[1,0,1]
	global_load_dword v96, v32, s[18:19]
	s_add_u32 s18, s18, 0x1000
	s_addc_u32 s19, s19, 0
	ds_read_b128 v[122:125], v63 offset:800
	s_waitcnt vmcnt(31) lgkmcnt(3)
	v_pk_fma_f32 v[40:41], v[126:127], v[96:97], v[40:41] op_sel:[0,1,0] op_sel_hi:[1,1,1]
	v_pk_fma_f32 v[42:43], v[128:129], v[96:97], v[42:43] op_sel:[0,1,0] op_sel_hi:[1,1,1]
	global_load_dword v97, v32, s[18:19]
	s_add_u32 s18, s18, 0x1000
	s_addc_u32 s19, s19, 0
	ds_read_b128 v[126:129], v63 offset:816
	s_waitcnt vmcnt(31) lgkmcnt(3)
	v_pk_fma_f32 v[40:41], v[114:115], v[98:99], v[40:41] op_sel_hi:[1,0,1]
	v_pk_fma_f32 v[42:43], v[116:117], v[98:99], v[42:43] op_sel_hi:[1,0,1]
	global_load_dword v98, v32, s[18:19]
	s_add_u32 s18, s18, 0x1000
	s_addc_u32 s19, s19, 0
	ds_read_b128 v[114:117], v63 offset:832
	s_waitcnt vmcnt(31) lgkmcnt(3)
	v_pk_fma_f32 v[40:41], v[118:119], v[98:99], v[40:41] op_sel:[0,1,0] op_sel_hi:[1,1,1]
	v_pk_fma_f32 v[42:43], v[120:121], v[98:99], v[42:43] op_sel:[0,1,0] op_sel_hi:[1,1,1]
	global_load_dword v99, v32, s[18:19]
	s_add_u32 s18, s18, 0x1000
	s_addc_u32 s19, s19, 0
	ds_read_b128 v[118:121], v63 offset:848
	s_waitcnt vmcnt(31) lgkmcnt(3)
	v_pk_fma_f32 v[40:41], v[122:123], v[100:101], v[40:41] op_sel_hi:[1,0,1]
	v_pk_fma_f32 v[42:43], v[124:125], v[100:101], v[42:43] op_sel_hi:[1,0,1]
	global_load_dword v100, v32, s[18:19]
	s_add_u32 s18, s18, 0x1000
	s_addc_u32 s19, s19, 0
	ds_read_b128 v[122:125], v63 offset:864
	s_waitcnt vmcnt(31) lgkmcnt(3)
	v_pk_fma_f32 v[40:41], v[126:127], v[100:101], v[40:41] op_sel:[0,1,0] op_sel_hi:[1,1,1]
	v_pk_fma_f32 v[42:43], v[128:129], v[100:101], v[42:43] op_sel:[0,1,0] op_sel_hi:[1,1,1]
	global_load_dword v101, v32, s[18:19]
	s_add_u32 s18, s18, 0x1000
	s_addc_u32 s19, s19, 0
	ds_read_b128 v[126:129], v63 offset:880
	s_waitcnt vmcnt(31) lgkmcnt(3)
	v_pk_fma_f32 v[40:41], v[114:115], v[102:103], v[40:41] op_sel_hi:[1,0,1]
	v_pk_fma_f32 v[42:43], v[116:117], v[102:103], v[42:43] op_sel_hi:[1,0,1]
	global_load_dword v102, v32, s[18:19]
	s_add_u32 s18, s18, 0x1000
	s_addc_u32 s19, s19, 0
	ds_read_b128 v[114:117], v63 offset:896
	s_waitcnt vmcnt(31) lgkmcnt(3)
	v_pk_fma_f32 v[40:41], v[118:119], v[102:103], v[40:41] op_sel:[0,1,0] op_sel_hi:[1,1,1]
	v_pk_fma_f32 v[42:43], v[120:121], v[102:103], v[42:43] op_sel:[0,1,0] op_sel_hi:[1,1,1]
	global_load_dword v103, v32, s[18:19]
	s_add_u32 s18, s18, 0x1000
	s_addc_u32 s19, s19, 0
	ds_read_b128 v[118:121], v63 offset:912
	s_waitcnt vmcnt(31) lgkmcnt(3)
	v_pk_fma_f32 v[40:41], v[122:123], v[104:105], v[40:41] op_sel_hi:[1,0,1]
	v_pk_fma_f32 v[42:43], v[124:125], v[104:105], v[42:43] op_sel_hi:[1,0,1]
	global_load_dword v104, v32, s[18:19]
	s_add_u32 s18, s18, 0x1000
	s_addc_u32 s19, s19, 0
	ds_read_b128 v[122:125], v63 offset:928
	s_waitcnt vmcnt(31) lgkmcnt(3)
; #define LAS __attribute__((address_space(3)))
; __global__ void __launch_bounds__(NTHREADS, 2) mk_fwd(Args args) {
;     ...
;                 for (int d0 = 0; d0 < 128; d0 += 32) {
;                     float wv[32];
; #pragma unroll
;                     for (int d = 0; d < 32; ++d) wv[d] = wpo[(size_t)(g * 128 + d0 + d) * DM + n];
; #pragma unroll
;                     for (int d = 0; d < 32; d += 4)
; #pragma unroll
;                         for (int j = 0; j < 4; ++j) { const f32x4 pv = *(const LAS f32x4*)(scr + j * 128 + d0 + d); a4[j] += (pv.x * wv[d] + pv.y * wv[d + 1]) + (pv.z * wv[d + 2] + pv.w * wv[d + 3]); } }
	v_pk_fma_f32 v[40:41], v[126:127], v[104:105], v[40:41] op_sel:[0,1,0] op_sel_hi:[1,1,1]
	v_pk_fma_f32 v[42:43], v[128:129], v[104:105], v[42:43] op_sel:[0,1,0] op_sel_hi:[1,1,1]
	global_load_dword v105, v32, s[18:19]
	s_add_u32 s18, s18, 0x1000
	s_addc_u32 s19, s19, 0
	ds_read_b128 v[126:129], v63 offset:944
	s_waitcnt vmcnt(31) lgkmcnt(3)
	v_pk_fma_f32 v[40:41], v[114:115], v[106:107], v[40:41] op_sel_hi:[1,0,1]
	v_pk_fma_f32 v[42:43], v[116:117], v[106:107], v[42:43] op_sel_hi:[1,0,1]
	global_load_dword v106, v32, s[18:19]
	s_add_u32 s18, s18, 0x1000
	s_addc_u32 s19, s19, 0
	ds_read_b128 v[114:117], v63 offset:960
	s_waitcnt vmcnt(31) lgkmcnt(3)
	v_pk_fma_f32 v[40:41], v[118:119], v[106:107], v[40:41] op_sel:[0,1,0] op_sel_hi:[1,1,1]
	v_pk_fma_f32 v[42:43], v[120:121], v[106:107], v[42:43] op_sel:[0,1,0] op_sel_hi:[1,1,1]
	global_load_dword v107, v32, s[18:19]
	s_add_u32 s18, s18, 0x1000
	s_addc_u32 s19, s19, 0
	ds_read_b128 v[118:121], v63 offset:976
	s_waitcnt vmcnt(31) lgkmcnt(3)
	v_pk_fma_f32 v[40:41], v[122:123], v[108:109], v[40:41] op_sel_hi:[1,0,1]
	v_pk_fma_f32 v[42:43], v[124:125], v[108:109], v[42:43] op_sel_hi:[1,0,1]
	global_load_dword v108, v32, s[18:19]
	s_add_u32 s18, s18, 0x1000
	s_addc_u32 s19, s19, 0
	ds_read_b128 v[122:125], v63 offset:992
	s_waitcnt vmcnt(31) lgkmcnt(3)
	v_pk_fma_f32 v[40:41], v[126:127], v[108:109], v[40:41] op_sel:[0,1,0] op_sel_hi:[1,1,1]
	v_pk_fma_f32 v[42:43], v[128:129], v[108:109], v[42:43] op_sel:[0,1,0] op_sel_hi:[1,1,1]
	global_load_dword v109, v32, s[18:19]
	s_add_u32 s18, s18, 0x1000
	s_addc_u32 s19, s19, 0
	ds_read_b128 v[126:129], v63 offset:1008
	s_waitcnt vmcnt(31) lgkmcnt(3)
	v_pk_fma_f32 v[40:41], v[114:115], v[110:111], v[40:41] op_sel_hi:[1,0,1]
	v_pk_fma_f32 v[42:43], v[116:117], v[110:111], v[42:43] op_sel_hi:[1,0,1]
	global_load_dword v110, v32, s[18:19]
	s_add_u32 s18, s18, 0x1000
	s_addc_u32 s19, s19, 0
	ds_read_b128 v[114:117], v63 offset:1024
	s_waitcnt vmcnt(31) lgkmcnt(3)
	v_pk_fma_f32 v[40:41], v[118:119], v[110:111], v[40:41] op_sel:[0,1,0] op_sel_hi:[1,1,1]
	v_pk_fma_f32 v[42:43], v[120:121], v[110:111], v[42:43] op_sel:[0,1,0] op_sel_hi:[1,1,1]
	global_load_dword v111, v32, s[18:19]
	s_add_u32 s18, s18, 0x1000
	s_addc_u32 s19, s19, 0
	ds_read_b128 v[118:121], v63 offset:1040
	s_waitcnt vmcnt(31) lgkmcnt(3)
	v_pk_fma_f32 v[40:41], v[122:123], v[112:113], v[40:41] op_sel_hi:[1,0,1]
	v_pk_fma_f32 v[42:43], v[124:125], v[112:113], v[42:43] op_sel_hi:[1,0,1]
	global_load_dword v112, v32, s[18:19]
	s_add_u32 s18, s18, 0x1000
	s_addc_u32 s19, s19, 0
	ds_read_b128 v[122:125], v63 offset:1056
	s_waitcnt vmcnt(31) lgkmcnt(3)
	v_pk_fma_f32 v[40:41], v[126:127], v[112:113], v[40:41] op_sel:[0,1,0] op_sel_hi:[1,1,1]
	v_pk_fma_f32 v[42:43], v[128:129], v[112:113], v[42:43] op_sel:[0,1,0] op_sel_hi:[1,1,1]
	global_load_dword v113, v32, s[18:19]
	s_add_u32 s18, s18, 0x1000
	s_addc_u32 s19, s19, 0
	ds_read_b128 v[126:129], v63 offset:1072
	s_waitcnt vmcnt(31) lgkmcnt(3)
	v_pk_fma_f32 v[40:41], v[114:115], v[82:83], v[40:41] op_sel_hi:[1,0,1]
	v_pk_fma_f32 v[42:43], v[116:117], v[82:83], v[42:43] op_sel_hi:[1,0,1]
	global_load_dword v82, v32, s[18:19]
	s_add_u32 s18, s18, 0x1000
	s_addc_u32 s19, s19, 0
	ds_read_b128 v[114:117], v63 offset:1088
	s_waitcnt vmcnt(31) lgkmcnt(3)
	v_pk_fma_f32 v[40:41], v[118:119], v[82:83], v[40:41] op_sel:[0,1,0] op_sel_hi:[1,1,1]
	v_pk_fma_f32 v[42:43], v[120:121], v[82:83], v[42:43] op_sel:[0,1,0] op_sel_hi:[1,1,1]
	global_load_dword v83, v32, s[18:19]
	s_add_u32 s18, s18, 0x1000
	s_addc_u32 s19, s19, 0
	ds_read_b128 v[118:121], v63 offset:1104
	s_waitcnt vmcnt(31) lgkmcnt(3)
	v_pk_fma_f32 v[40:41], v[122:123], v[84:85], v[40:41] op_sel_hi:[1,0,1]
	v_pk_fma_f32 v[42:43], v[124:125], v[84:85], v[42:43] op_sel_hi:[1,0,1]
	global_load_dword v84, v32, s[18:19]
	s_add_u32 s18, s18, 0x1000
	s_addc_u32 s19, s19, 0
	ds_read_b128 v[122:125], v63 offset:1120
	s_waitcnt vmcnt(31) lgkmcnt(3)
	v_pk_fma_f32 v[40:41], v[126:127], v[84:85], v[40:41] op_sel:[0,1,0] op_sel_hi:[1,1,1]
	v_pk_fma_f32 v[42:43], v[128:129], v[84:85], v[42:43] op_sel:[0,1,0] op_sel_hi:[1,1,1]
	global_load_dword v85, v32, s[18:19]
	s_add_u32 s18, s18, 0x1000
	s_addc_u32 s19, s19, 0
	ds_read_b128 v[126:129], v63 offset:1136
	s_waitcnt vmcnt(31) lgkmcnt(3)
	v_pk_fma_f32 v[40:41], v[114:115], v[86:87], v[40:41] op_sel_hi:[1,0,1]
	v_pk_fma_f32 v[42:43], v[116:117], v[86:87], v[42:43] op_sel_hi:[1,0,1]
	global_load_dword v86, v32, s[18:19]
	s_add_u32 s18, s18, 0x1000
	s_addc_u32 s19, s19, 0
	ds_read_b128 v[114:117], v63 offset:1152
	s_waitcnt vmcnt(31) lgkmcnt(3)
	v_pk_fma_f32 v[40:41], v[118:119], v[86:87], v[40:41] op_sel:[0,1,0] op_sel_hi:[1,1,1]
	v_pk_fma_f32 v[42:43], v[120:121], v[86:87], v[42:43] op_sel:[0,1,0] op_sel_hi:[1,1,1]
	global_load_dword v87, v32, s[18:19]
	s_add_u32 s18, s18, 0x1000
	s_addc_u32 s19, s19, 0
	ds_read_b128 v[118:121], v63 offset:1168
	s_waitcnt vmcnt(31) lgkmcnt(3)
	v_pk_fma_f32 v[40:41], v[122:123], v[88:89], v[40:41] op_sel_hi:[1,0,1]
	v_pk_fma_f32 v[42:43], v[124:125], v[88:89], v[42:43] op_sel_hi:[1,0,1]
	global_load_dword v88, v32, s[18:19]
	s_add_u32 s18, s18, 0x1000
	s_addc_u32 s19, s19, 0
	ds_read_b128 v[122:125], v63 offset:1184
	s_waitcnt vmcnt(31) lgkmcnt(3)
	v_pk_fma_f32 v[40:41], v[126:127], v[88:89], v[40:41] op_sel:[0,1,0] op_sel_hi:[1,1,1]
	v_pk_fma_f32 v[42:43], v[128:129], v[88:89], v[42:43] op_sel:[0,1,0] op_sel_hi:[1,1,1]
	global_load_dword v89, v32, s[18:19]
	s_add_u32 s18, s18, 0x1000
	s_addc_u32 s19, s19, 0
	ds_read_b128 v[126:129], v63 offset:1200
	s_waitcnt vmcnt(31) lgkmcnt(3)
; #define LAS __attribute__((address_space(3)))
; __global__ void __launch_bounds__(NTHREADS, 2) mk_fwd(Args args) {
;     ...
;                 for (int d0 = 0; d0 < 128; d0 += 32) {
;                     float wv[32];
; #pragma unroll
;                     for (int d = 0; d < 32; ++d) wv[d] = wpo[(size_t)(g * 128 + d0 + d) * DM + n];
; #pragma unroll
;                     for (int d = 0; d < 32; d += 4)
; #pragma unroll
;                         for (int j = 0; j < 4; ++j) { const f32x4 pv = *(const LAS f32x4*)(scr + j * 128 + d0 + d); a4[j] += (pv.x * wv[d] + pv.y * wv[d + 1]) + (pv.z * wv[d + 2] + pv.w * wv[d + 3]); } }
	v_pk_fma_f32 v[40:41], v[114:115], v[90:91], v[40:41] op_sel_hi:[1,0,1]
	v_pk_fma_f32 v[42:43], v[116:117], v[90:91], v[42:43] op_sel_hi:[1,0,1]
	global_load_dword v90, v32, s[18:19]
	s_add_u32 s18, s18, 0x1000
	s_addc_u32 s19, s19, 0
	ds_read_b128 v[114:117], v63 offset:1216
	s_waitcnt vmcnt(31) lgkmcnt(3)
	v_pk_fma_f32 v[40:41], v[118:119], v[90:91], v[40:41] op_sel:[0,1,0] op_sel_hi:[1,1,1]
	v_pk_fma_f32 v[42:43], v[120:121], v[90:91], v[42:43] op_sel:[0,1,0] op_sel_hi:[1,1,1]
	global_load_dword v91, v32, s[18:19]
	s_add_u32 s18, s18, 0x1000
	s_addc_u32 s19, s19, 0
	ds_read_b128 v[118:121], v63 offset:1232
	s_waitcnt vmcnt(31) lgkmcnt(3)
	v_pk_fma_f32 v[40:41], v[122:123], v[92:93], v[40:41] op_sel_hi:[1,0,1]
	v_pk_fma_f32 v[42:43], v[124:125], v[92:93], v[42:43] op_sel_hi:[1,0,1]
	global_load_dword v92, v32, s[18:19]
	s_add_u32 s18, s18, 0x1000
	s_addc_u32 s19, s19, 0
	ds_read_b128 v[122:125], v63 offset:1248
	s_waitcnt vmcnt(31) lgkmcnt(3)
	v_pk_fma_f32 v[40:41], v[126:127], v[92:93], v[40:41] op_sel:[0,1,0] op_sel_hi:[1,1,1]
	v_pk_fma_f32 v[42:43], v[128:129], v[92:93], v[42:43] op_sel:[0,1,0] op_sel_hi:[1,1,1]
	global_load_dword v93, v32, s[18:19]
	s_add_u32 s18, s18, 0x1000
	s_addc_u32 s19, s19, 0
	ds_read_b128 v[126:129], v63 offset:1264
	s_waitcnt vmcnt(31) lgkmcnt(3)
	v_pk_fma_f32 v[40:41], v[114:115], v[94:95], v[40:41] op_sel_hi:[1,0,1]
	v_pk_fma_f32 v[42:43], v[116:117], v[94:95], v[42:43] op_sel_hi:[1,0,1]
	global_load_dword v94, v32, s[18:19]
	s_add_u32 s18, s18, 0x1000
	s_addc_u32 s19, s19, 0
	ds_read_b128 v[114:117], v63 offset:1280
	s_waitcnt vmcnt(31) lgkmcnt(3)
	v_pk_fma_f32 v[40:41], v[118:119], v[94:95], v[40:41] op_sel:[0,1,0] op_sel_hi:[1,1,1]
	v_pk_fma_f32 v[42:43], v[120:121], v[94:95], v[42:43] op_sel:[0,1,0] op_sel_hi:[1,1,1]
	global_load_dword v95, v32, s[18:19]
	s_add_u32 s18, s18, 0x1000
	s_addc_u32 s19, s19, 0
	ds_read_b128 v[118:121], v63 offset:1296
	s_waitcnt vmcnt(31) lgkmcnt(3)
	v_pk_fma_f32 v[40:41], v[122:123], v[96:97], v[40:41] op_sel_hi:[1,0,1]
	v_pk_fma_f32 v[42:43], v[124:125], v[96:97], v[42:43] op_sel_hi:[1,0,1]
	global_load_dword v96, v32, s[18:19]
	s_add_u32 s18, s18, 0x1000
	s_addc_u32 s19, s19, 0
	ds_read_b128 v[122:125], v63 offset:1312
	s_waitcnt vmcnt(31) lgkmcnt(3)
	v_pk_fma_f32 v[40:41], v[126:127], v[96:97], v[40:41] op_sel:[0,1,0] op_sel_hi:[1,1,1]
	v_pk_fma_f32 v[42:43], v[128:129], v[96:97], v[42:43] op_sel:[0,1,0] op_sel_hi:[1,1,1]
	global_load_dword v97, v32, s[18:19]
	s_add_u32 s18, s18, 0x1000
	s_addc_u32 s19, s19, 0
	ds_read_b128 v[126:129], v63 offset:1328
	s_waitcnt vmcnt(31) lgkmcnt(3)
	v_pk_fma_f32 v[40:41], v[114:115], v[98:99], v[40:41] op_sel_hi:[1,0,1]
	v_pk_fma_f32 v[42:43], v[116:117], v[98:99], v[42:43] op_sel_hi:[1,0,1]
	global_load_dword v98, v32, s[18:19]
	s_add_u32 s18, s18, 0x1000
	s_addc_u32 s19, s19, 0
	ds_read_b128 v[114:117], v63 offset:1344
	s_waitcnt vmcnt(31) lgkmcnt(3)
	v_pk_fma_f32 v[40:41], v[118:119], v[98:99], v[40:41] op_sel:[0,1,0] op_sel_hi:[1,1,1]
	v_pk_fma_f32 v[42:43], v[120:121], v[98:99], v[42:43] op_sel:[0,1,0] op_sel_hi:[1,1,1]
	global_load_dword v99, v32, s[18:19]
	s_add_u32 s18, s18, 0x1000
	s_addc_u32 s19, s19, 0
	ds_read_b128 v[118:121], v63 offset:1360
	s_waitcnt vmcnt(31) lgkmcnt(3)
	v_pk_fma_f32 v[40:41], v[122:123], v[100:101], v[40:41] op_sel_hi:[1,0,1]
	v_pk_fma_f32 v[42:43], v[124:125], v[100:101], v[42:43] op_sel_hi:[1,0,1]
	global_load_dword v100, v32, s[18:19]
	s_add_u32 s18, s18, 0x1000
	s_addc_u32 s19, s19, 0
	ds_read_b128 v[122:125], v63 offset:1376
	s_waitcnt vmcnt(31) lgkmcnt(3)
	v_pk_fma_f32 v[40:41], v[126:127], v[100:101], v[40:41] op_sel:[0,1,0] op_sel_hi:[1,1,1]
	v_pk_fma_f32 v[42:43], v[128:129], v[100:101], v[42:43] op_sel:[0,1,0] op_sel_hi:[1,1,1]
	global_load_dword v101, v32, s[18:19]
	s_add_u32 s18, s18, 0x1000
	s_addc_u32 s19, s19, 0
	ds_read_b128 v[126:129], v63 offset:1392
	s_waitcnt vmcnt(31) lgkmcnt(3)
	v_pk_fma_f32 v[40:41], v[114:115], v[102:103], v[40:41] op_sel_hi:[1,0,1]
	v_pk_fma_f32 v[42:43], v[116:117], v[102:103], v[42:43] op_sel_hi:[1,0,1]
	global_load_dword v102, v32, s[18:19]
	s_add_u32 s18, s18, 0x1000
	s_addc_u32 s19, s19, 0
	ds_read_b128 v[114:117], v63 offset:1408
	s_waitcnt vmcnt(31) lgkmcnt(3)
	v_pk_fma_f32 v[40:41], v[118:119], v[102:103], v[40:41] op_sel:[0,1,0] op_sel_hi:[1,1,1]
	v_pk_fma_f32 v[42:43], v[120:121], v[102:103], v[42:43] op_sel:[0,1,0] op_sel_hi:[1,1,1]
	global_load_dword v103, v32, s[18:19]
	s_add_u32 s18, s18, 0x1000
	s_addc_u32 s19, s19, 0
	ds_read_b128 v[118:121], v63 offset:1424
	s_waitcnt vmcnt(31) lgkmcnt(3)
	v_pk_fma_f32 v[40:41], v[122:123], v[104:105], v[40:41] op_sel_hi:[1,0,1]
	v_pk_fma_f32 v[42:43], v[124:125], v[104:105], v[42:43] op_sel_hi:[1,0,1]
	global_load_dword v104, v32, s[18:19]
	s_add_u32 s18, s18, 0x1000
	s_addc_u32 s19, s19, 0
	ds_read_b128 v[122:125], v63 offset:1440
	s_waitcnt vmcnt(31) lgkmcnt(3)
	v_pk_fma_f32 v[40:41], v[126:127], v[104:105], v[40:41] op_sel:[0,1,0] op_sel_hi:[1,1,1]
	v_pk_fma_f32 v[42:43], v[128:129], v[104:105], v[42:43] op_sel:[0,1,0] op_sel_hi:[1,1,1]
	global_load_dword v105, v32, s[18:19]
	s_add_u32 s18, s18, 0x1000
	s_addc_u32 s19, s19, 0
	ds_read_b128 v[126:129], v63 offset:1456
	s_waitcnt vmcnt(31) lgkmcnt(3)
	v_pk_fma_f32 v[40:41], v[114:115], v[106:107], v[40:41] op_sel_hi:[1,0,1]
	v_pk_fma_f32 v[42:43], v[116:117], v[106:107], v[42:43] op_sel_hi:[1,0,1]
	global_load_dword v106, v32, s[18:19]
	s_add_u32 s18, s18, 0x1000
	s_addc_u32 s19, s19, 0
	ds_read_b128 v[114:117], v63 offset:1472
	s_waitcnt vmcnt(31) lgkmcnt(3)
; #define LAS __attribute__((address_space(3)))
; __global__ void __launch_bounds__(NTHREADS, 2) mk_fwd(Args args) {
;     ...
;                 for (int d0 = 0; d0 < 128; d0 += 32) {
;                     float wv[32];
; #pragma unroll
;                     for (int d = 0; d < 32; ++d) wv[d] = wpo[(size_t)(g * 128 + d0 + d) * DM + n];
; #pragma unroll
;                     for (int d = 0; d < 32; d += 4)
; #pragma unroll
;                         for (int j = 0; j < 4; ++j) { const f32x4 pv = *(const LAS f32x4*)(scr + j * 128 + d0 + d); a4[j] += (pv.x * wv[d] + pv.y * wv[d + 1]) + (pv.z * wv[d + 2] + pv.w * wv[d + 3]); } }
	v_pk_fma_f32 v[40:41], v[118:119], v[106:107], v[40:41] op_sel:[0,1,0] op_sel_hi:[1,1,1]
	v_pk_fma_f32 v[42:43], v[120:121], v[106:107], v[42:43] op_sel:[0,1,0] op_sel_hi:[1,1,1]
	global_load_dword v107, v32, s[18:19]
	s_add_u32 s18, s18, 0x1000
	s_addc_u32 s19, s19, 0
	ds_read_b128 v[118:121], v63 offset:1488
	s_waitcnt vmcnt(31) lgkmcnt(3)
	v_pk_fma_f32 v[40:41], v[122:123], v[108:109], v[40:41] op_sel_hi:[1,0,1]
	v_pk_fma_f32 v[42:43], v[124:125], v[108:109], v[42:43] op_sel_hi:[1,0,1]
	global_load_dword v108, v32, s[18:19]
	s_add_u32 s18, s18, 0x1000
	s_addc_u32 s19, s19, 0
	ds_read_b128 v[122:125], v63 offset:1504
	s_waitcnt vmcnt(31) lgkmcnt(3)
	v_pk_fma_f32 v[40:41], v[126:127], v[108:109], v[40:41] op_sel:[0,1,0] op_sel_hi:[1,1,1]
	v_pk_fma_f32 v[42:43], v[128:129], v[108:109], v[42:43] op_sel:[0,1,0] op_sel_hi:[1,1,1]
	global_load_dword v109, v32, s[18:19]
	s_add_u32 s18, s18, 0x1000
	s_addc_u32 s19, s19, 0
	ds_read_b128 v[126:129], v63 offset:1520
	s_waitcnt vmcnt(31) lgkmcnt(3)
	v_pk_fma_f32 v[40:41], v[114:115], v[110:111], v[40:41] op_sel_hi:[1,0,1]
	v_pk_fma_f32 v[42:43], v[116:117], v[110:111], v[42:43] op_sel_hi:[1,0,1]
	global_load_dword v110, v32, s[18:19]
	s_add_u32 s18, s18, 0x1000
	s_addc_u32 s19, s19, 0
	ds_read_b128 v[114:117], v63 offset:1536
	s_waitcnt vmcnt(31) lgkmcnt(3)
	v_pk_fma_f32 v[40:41], v[118:119], v[110:111], v[40:41] op_sel:[0,1,0] op_sel_hi:[1,1,1]
	v_pk_fma_f32 v[42:43], v[120:121], v[110:111], v[42:43] op_sel:[0,1,0] op_sel_hi:[1,1,1]
	global_load_dword v111, v32, s[18:19]
	s_add_u32 s18, s18, 0x1000
	s_addc_u32 s19, s19, 0
	ds_read_b128 v[118:121], v63 offset:1552
	s_waitcnt vmcnt(31) lgkmcnt(3)
	v_pk_fma_f32 v[40:41], v[122:123], v[112:113], v[40:41] op_sel_hi:[1,0,1]
	v_pk_fma_f32 v[42:43], v[124:125], v[112:113], v[42:43] op_sel_hi:[1,0,1]
	global_load_dword v112, v32, s[18:19]
	s_add_u32 s18, s18, 0x1000
	s_addc_u32 s19, s19, 0
	ds_read_b128 v[122:125], v63 offset:1568
	s_waitcnt vmcnt(31) lgkmcnt(3)
	v_pk_fma_f32 v[40:41], v[126:127], v[112:113], v[40:41] op_sel:[0,1,0] op_sel_hi:[1,1,1]
	v_pk_fma_f32 v[42:43], v[128:129], v[112:113], v[42:43] op_sel:[0,1,0] op_sel_hi:[1,1,1]
	global_load_dword v113, v32, s[18:19]
	s_add_u32 s18, s18, 0x1000
	s_addc_u32 s19, s19, 0
	ds_read_b128 v[126:129], v63 offset:1584
	s_waitcnt vmcnt(31) lgkmcnt(3)
	v_pk_fma_f32 v[40:41], v[114:115], v[82:83], v[40:41] op_sel_hi:[1,0,1]
	v_pk_fma_f32 v[42:43], v[116:117], v[82:83], v[42:43] op_sel_hi:[1,0,1]
	ds_read_b128 v[114:117], v63 offset:1600
	s_waitcnt vmcnt(30) lgkmcnt(3)
	v_pk_fma_f32 v[40:41], v[118:119], v[82:83], v[40:41] op_sel:[0,1,0] op_sel_hi:[1,1,1]
	v_pk_fma_f32 v[42:43], v[120:121], v[82:83], v[42:43] op_sel:[0,1,0] op_sel_hi:[1,1,1]
	ds_read_b128 v[118:121], v63 offset:1616
	s_waitcnt vmcnt(29) lgkmcnt(3)
	v_pk_fma_f32 v[40:41], v[122:123], v[84:85], v[40:41] op_sel_hi:[1,0,1]
	v_pk_fma_f32 v[42:43], v[124:125], v[84:85], v[42:43] op_sel_hi:[1,0,1]
	ds_read_b128 v[122:125], v63 offset:1632
	s_waitcnt vmcnt(28) lgkmcnt(3)
	v_pk_fma_f32 v[40:41], v[126:127], v[84:85], v[40:41] op_sel:[0,1,0] op_sel_hi:[1,1,1]
	v_pk_fma_f32 v[42:43], v[128:129], v[84:85], v[42:43] op_sel:[0,1,0] op_sel_hi:[1,1,1]
	ds_read_b128 v[126:129], v63 offset:1648
	s_waitcnt vmcnt(27) lgkmcnt(3)
	v_pk_fma_f32 v[40:41], v[114:115], v[86:87], v[40:41] op_sel_hi:[1,0,1]
	v_pk_fma_f32 v[42:43], v[116:117], v[86:87], v[42:43] op_sel_hi:[1,0,1]
	ds_read_b128 v[114:117], v63 offset:1664
	s_waitcnt vmcnt(26) lgkmcnt(3)
	v_pk_fma_f32 v[40:41], v[118:119], v[86:87], v[40:41] op_sel:[0,1,0] op_sel_hi:[1,1,1]
	v_pk_fma_f32 v[42:43], v[120:121], v[86:87], v[42:43] op_sel:[0,1,0] op_sel_hi:[1,1,1]
	ds_read_b128 v[118:121], v63 offset:1680
	s_waitcnt vmcnt(25) lgkmcnt(3)
	v_pk_fma_f32 v[40:41], v[122:123], v[88:89], v[40:41] op_sel_hi:[1,0,1]
	v_pk_fma_f32 v[42:43], v[124:125], v[88:89], v[42:43] op_sel_hi:[1,0,1]
	ds_read_b128 v[122:125], v63 offset:1696
	s_waitcnt vmcnt(24) lgkmcnt(3)
	v_pk_fma_f32 v[40:41], v[126:127], v[88:89], v[40:41] op_sel:[0,1,0] op_sel_hi:[1,1,1]
	v_pk_fma_f32 v[42:43], v[128:129], v[88:89], v[42:43] op_sel:[0,1,0] op_sel_hi:[1,1,1]
	ds_read_b128 v[126:129], v63 offset:1712
	s_waitcnt vmcnt(23) lgkmcnt(3)
	v_pk_fma_f32 v[40:41], v[114:115], v[90:91], v[40:41] op_sel_hi:[1,0,1]
	v_pk_fma_f32 v[42:43], v[116:117], v[90:91], v[42:43] op_sel_hi:[1,0,1]
	ds_read_b128 v[114:117], v63 offset:1728
	s_waitcnt vmcnt(22) lgkmcnt(3)
	v_pk_fma_f32 v[40:41], v[118:119], v[90:91], v[40:41] op_sel:[0,1,0] op_sel_hi:[1,1,1]
	v_pk_fma_f32 v[42:43], v[120:121], v[90:91], v[42:43] op_sel:[0,1,0] op_sel_hi:[1,1,1]
	ds_read_b128 v[118:121], v63 offset:1744
	s_waitcnt vmcnt(21) lgkmcnt(3)
	v_pk_fma_f32 v[40:41], v[122:123], v[92:93], v[40:41] op_sel_hi:[1,0,1]
	v_pk_fma_f32 v[42:43], v[124:125], v[92:93], v[42:43] op_sel_hi:[1,0,1]
	ds_read_b128 v[122:125], v63 offset:1760
	s_waitcnt vmcnt(20) lgkmcnt(3)
	v_pk_fma_f32 v[40:41], v[126:127], v[92:93], v[40:41] op_sel:[0,1,0] op_sel_hi:[1,1,1]
	v_pk_fma_f32 v[42:43], v[128:129], v[92:93], v[42:43] op_sel:[0,1,0] op_sel_hi:[1,1,1]
	ds_read_b128 v[126:129], v63 offset:1776
	s_waitcnt vmcnt(19) lgkmcnt(3)
; #define LAS __attribute__((address_space(3)))
; #define LDS_WAIT() asm volatile("s_waitcnt lgkmcnt(0)" ::: "memory")
; __global__ void __launch_bounds__(NTHREADS, 2) mk_fwd(Args args) {
;     ...
;                 for (int d0 = 0; d0 < 128; d0 += 32) {
;                     float wv[32];
; #pragma unroll
;                     for (int d = 0; d < 32; ++d) wv[d] = wpo[(size_t)(g * 128 + d0 + d) * DM + n];
; #pragma unroll
;                     for (int d = 0; d < 32; d += 4)
; #pragma unroll
;                         for (int j = 0; j < 4; ++j) { const f32x4 pv = *(const LAS f32x4*)(scr + j * 128 + d0 + d); a4[j] += (pv.x * wv[d] + pv.y * wv[d + 1]) + (pv.z * wv[d + 2] + pv.w * wv[d + 3]); } }
;                 u32x2 o; o.x = rd<D_WMIX>(pk_f16(a4[0], a4[1])); o.y = rd<D_WMIX>(pk_f16(a4[2], a4[3]));
;                 *(u32x2*)((f16*)(ws + W_PC) + (size_t)n * DP + k0) = o;
;                 LDS_WAIT(); asm volatile("" ::: "memory");
	v_pk_fma_f32 v[40:41], v[114:115], v[94:95], v[40:41] op_sel_hi:[1,0,1]
	v_pk_fma_f32 v[42:43], v[116:117], v[94:95], v[42:43] op_sel_hi:[1,0,1]
	ds_read_b128 v[114:117], v63 offset:1792
	s_waitcnt vmcnt(18) lgkmcnt(3)
	v_pk_fma_f32 v[40:41], v[118:119], v[94:95], v[40:41] op_sel:[0,1,0] op_sel_hi:[1,1,1]
	v_pk_fma_f32 v[42:43], v[120:121], v[94:95], v[42:43] op_sel:[0,1,0] op_sel_hi:[1,1,1]
	ds_read_b128 v[118:121], v63 offset:1808
	s_waitcnt vmcnt(17) lgkmcnt(3)
	v_pk_fma_f32 v[40:41], v[122:123], v[96:97], v[40:41] op_sel_hi:[1,0,1]
	v_pk_fma_f32 v[42:43], v[124:125], v[96:97], v[42:43] op_sel_hi:[1,0,1]
	ds_read_b128 v[122:125], v63 offset:1824
	s_waitcnt vmcnt(16) lgkmcnt(3)
	v_pk_fma_f32 v[40:41], v[126:127], v[96:97], v[40:41] op_sel:[0,1,0] op_sel_hi:[1,1,1]
	v_pk_fma_f32 v[42:43], v[128:129], v[96:97], v[42:43] op_sel:[0,1,0] op_sel_hi:[1,1,1]
	ds_read_b128 v[126:129], v63 offset:1840
	s_waitcnt vmcnt(15) lgkmcnt(3)
	v_pk_fma_f32 v[40:41], v[114:115], v[98:99], v[40:41] op_sel_hi:[1,0,1]
	v_pk_fma_f32 v[42:43], v[116:117], v[98:99], v[42:43] op_sel_hi:[1,0,1]
	ds_read_b128 v[114:117], v63 offset:1856
	s_waitcnt vmcnt(14) lgkmcnt(3)
	v_pk_fma_f32 v[40:41], v[118:119], v[98:99], v[40:41] op_sel:[0,1,0] op_sel_hi:[1,1,1]
	v_pk_fma_f32 v[42:43], v[120:121], v[98:99], v[42:43] op_sel:[0,1,0] op_sel_hi:[1,1,1]
	ds_read_b128 v[118:121], v63 offset:1872
	s_waitcnt vmcnt(13) lgkmcnt(3)
	v_pk_fma_f32 v[40:41], v[122:123], v[100:101], v[40:41] op_sel_hi:[1,0,1]
	v_pk_fma_f32 v[42:43], v[124:125], v[100:101], v[42:43] op_sel_hi:[1,0,1]
	ds_read_b128 v[122:125], v63 offset:1888
	s_waitcnt vmcnt(12) lgkmcnt(3)
	v_pk_fma_f32 v[40:41], v[126:127], v[100:101], v[40:41] op_sel:[0,1,0] op_sel_hi:[1,1,1]
	v_pk_fma_f32 v[42:43], v[128:129], v[100:101], v[42:43] op_sel:[0,1,0] op_sel_hi:[1,1,1]
	ds_read_b128 v[126:129], v63 offset:1904
	s_waitcnt vmcnt(11) lgkmcnt(3)
	v_pk_fma_f32 v[40:41], v[114:115], v[102:103], v[40:41] op_sel_hi:[1,0,1]
	v_pk_fma_f32 v[42:43], v[116:117], v[102:103], v[42:43] op_sel_hi:[1,0,1]
	ds_read_b128 v[114:117], v63 offset:1920
	s_waitcnt vmcnt(10) lgkmcnt(3)
	v_pk_fma_f32 v[40:41], v[118:119], v[102:103], v[40:41] op_sel:[0,1,0] op_sel_hi:[1,1,1]
	v_pk_fma_f32 v[42:43], v[120:121], v[102:103], v[42:43] op_sel:[0,1,0] op_sel_hi:[1,1,1]
	ds_read_b128 v[118:121], v63 offset:1936
	s_waitcnt vmcnt(9) lgkmcnt(3)
	v_pk_fma_f32 v[40:41], v[122:123], v[104:105], v[40:41] op_sel_hi:[1,0,1]
	v_pk_fma_f32 v[42:43], v[124:125], v[104:105], v[42:43] op_sel_hi:[1,0,1]
	ds_read_b128 v[122:125], v63 offset:1952
	s_waitcnt vmcnt(8) lgkmcnt(3)
	v_pk_fma_f32 v[40:41], v[126:127], v[104:105], v[40:41] op_sel:[0,1,0] op_sel_hi:[1,1,1]
	v_pk_fma_f32 v[42:43], v[128:129], v[104:105], v[42:43] op_sel:[0,1,0] op_sel_hi:[1,1,1]
	ds_read_b128 v[126:129], v63 offset:1968
	s_waitcnt vmcnt(7) lgkmcnt(3)
	v_pk_fma_f32 v[40:41], v[114:115], v[106:107], v[40:41] op_sel_hi:[1,0,1]
	v_pk_fma_f32 v[42:43], v[116:117], v[106:107], v[42:43] op_sel_hi:[1,0,1]
	ds_read_b128 v[114:117], v63 offset:1984
	s_waitcnt vmcnt(6) lgkmcnt(3)
	v_pk_fma_f32 v[40:41], v[118:119], v[106:107], v[40:41] op_sel:[0,1,0] op_sel_hi:[1,1,1]
	v_pk_fma_f32 v[42:43], v[120:121], v[106:107], v[42:43] op_sel:[0,1,0] op_sel_hi:[1,1,1]
	ds_read_b128 v[118:121], v63 offset:2000
	s_waitcnt vmcnt(5) lgkmcnt(3)
	v_pk_fma_f32 v[40:41], v[122:123], v[108:109], v[40:41] op_sel_hi:[1,0,1]
	v_pk_fma_f32 v[42:43], v[124:125], v[108:109], v[42:43] op_sel_hi:[1,0,1]
	ds_read_b128 v[122:125], v63 offset:2016
	s_waitcnt vmcnt(4) lgkmcnt(3)
	v_pk_fma_f32 v[40:41], v[126:127], v[108:109], v[40:41] op_sel:[0,1,0] op_sel_hi:[1,1,1]
	v_pk_fma_f32 v[42:43], v[128:129], v[108:109], v[42:43] op_sel:[0,1,0] op_sel_hi:[1,1,1]
	ds_read_b128 v[126:129], v63 offset:2032
	s_waitcnt vmcnt(3) lgkmcnt(3)
	v_pk_fma_f32 v[40:41], v[114:115], v[110:111], v[40:41] op_sel_hi:[1,0,1]
	v_pk_fma_f32 v[42:43], v[116:117], v[110:111], v[42:43] op_sel_hi:[1,0,1]
	s_waitcnt vmcnt(2) lgkmcnt(2)
	v_pk_fma_f32 v[40:41], v[118:119], v[110:111], v[40:41] op_sel:[0,1,0] op_sel_hi:[1,1,1]
	v_pk_fma_f32 v[42:43], v[120:121], v[110:111], v[42:43] op_sel:[0,1,0] op_sel_hi:[1,1,1]
	s_waitcnt vmcnt(1) lgkmcnt(1)
	v_pk_fma_f32 v[40:41], v[122:123], v[112:113], v[40:41] op_sel_hi:[1,0,1]
	v_pk_fma_f32 v[42:43], v[124:125], v[112:113], v[42:43] op_sel_hi:[1,0,1]
	s_waitcnt vmcnt(0) lgkmcnt(0)
	v_pk_fma_f32 v[40:41], v[126:127], v[112:113], v[40:41] op_sel:[0,1,0] op_sel_hi:[1,1,1]
	v_pk_fma_f32 v[42:43], v[128:129], v[112:113], v[42:43] op_sel:[0,1,0] op_sel_hi:[1,1,1]
	s_lshl_b32 s17, s15, 6
	s_and_b32 s17, s17, 0x3c0
	v_or_b32_e32 v32, s17, v71
	v_readlane_b32 s18, v252, 1
	v_cvt_pk_f16_f32 v38, v40, v41
	v_cvt_pk_f16_f32 v39, v42, v43
	v_lshlrev_b32_e32 v32, 10, v32
	v_readlane_b32 s19, v252, 2
	v_add_u32_e32 v38, 0x100010, v38
	v_add_u32_e32 v39, 0x100010, v39
	v_lshl_add_u64 v[40:41], s[18:19], 0, v[32:33]
	v_and_b32_e32 v38, 0xffe0ffe0, v38
	v_and_b32_e32 v39, 0xffe0ffe0, v39
	v_lshl_add_u64 v[40:41], s[2:3], 1, v[40:41]
	global_store_dwordx2 v[40:41], v[38:39], off
	s_waitcnt lgkmcnt(0)
	s_add_i32 s15, s15, s64
	s_add_i32 s14, s14, s78
	s_cmpk_gt_i32 s15, 0x7ff
	s_cbranch_scc0 .LBB0_617
